# row_pass2 (all-bf16 rows): 16-byte per-lane loads/stores (lane owns 8 consecutive elements) instead of 8-byte ones
# baseline (speedup 1.0000x reference)
; __device__ __forceinline__ unsigned cvtpk(float lo, float hi) { f32x2_t v = {lo, hi}; bf16x2_t b = __builtin_convertvector(v, bf16x2_t); return __builtin_bit_cast(unsigned, b); }
; #define NTL(p) __builtin_nontemporal_load(&(p))
; template <bool HAS_H, bool XIN_BF, bool XOUT_BF>
; __device__ __forceinline__ void row_pass(const bf16_t* y, const void* xin, void* xout, const float* g_post, const float* g_pre, bf16_t* hout, int G, int blk) {
;     ...
;     for (int row = gw; row < MT; row += NGW) {
;         const u32x2* yr = (const u32x2*)(y + (size_t)row * DM) + lane;
;         const f32x4* xr = (const f32x4*)((const float*)xin + (size_t)row * DM) + lane;
;         const u32x2* xrb = (const u32x2*)((const bf16_t*)xin + (size_t)row * DM) + lane;
;         f32x4 yv[8], xv[8]; float s = 0.f;
; #pragma unroll
;         for (int j = 0; j < 8; ++j) { const u32x2 w = NTL(yr[64 * j]); yv[j] = (f32x4){bf_lo(w.x), bf_hi(w.x), bf_lo(w.y), bf_hi(w.y)};
;             if (XIN_BF) { const u32x2 xw = NTL(xrb[64 * j]); xv[j] = (f32x4){bf_lo(xw.x), bf_hi(xw.x), bf_lo(xw.y), bf_hi(xw.y)}; } else xv[j] = NTL(xr[64 * j]);
;             s += (yv[j].x * yv[j].x + yv[j].y * yv[j].y) + (yv[j].z * yv[j].z + yv[j].w * yv[j].w); }
;         const float r = 1.0f / sqrtf(wave_sum(s) * (1.0f / DM) + EPS);
;         const f32x4* gp = (const f32x4*)g_post + lane;
;         f32x4* xo = (f32x4*)((float*)xout + (size_t)row * DM) + lane;
;         u32x2* xob = (u32x2*)((bf16_t*)xout + (size_t)row * DM) + lane;
;         float s1 = 0.f;
; #pragma unroll
;         for (int j = 0; j < 8; ++j) { const f32x4 gv = gp[64 * j]; xv[j] = xv[j] + yv[j] * r * gv;
;             if (XOUT_BF) { u32x2 w; w.x = cvtpk(xv[j].x, xv[j].y); w.y = cvtpk(xv[j].z, xv[j].w); NTS(w, xob[64 * j]); } else NTS(xv[j], xo[64 * j]);
;             s1 += (xv[j].x * xv[j].x + xv[j].y * xv[j].y) + (xv[j].z * xv[j].z + xv[j].w * xv[j].w); }
;         if (HAS_H) {
;             const float r1 = 1.0f / sqrtf(wave_sum(s1) * (1.0f / DM) + EPS);
;             const f32x4* gq = (const f32x4*)g_pre + lane;
;             u32x2* ho = (u32x2*)(hout + (size_t)row * DM) + lane;
; #pragma unroll
;             for (int j = 0; j < 8; ++j) { const f32x4 gv = gq[64 * j]; u32x2 w; w.x = cvtpk(xv[j].x * r1 * gv.x, xv[j].y * r1 * gv.y); w.y = cvtpk(xv[j].z * r1 * gv.z, xv[j].w * r1 * gv.w); ho[64 * j] = w; }
.LBB0_758:
	v_readfirstlane_b32 s32, v128
	s_nop 3
	v_lshlrev_b32_e32 v4, 3, v163
	v_lshlrev_b32_e32 v5, 4, v163
	v_mov_b32_e32 v6, 0x358637bd
	v_mov_b32_e32 v7, 0x260
	s_mov_b32 s85, 0xf800000
	v_xor_b32_e32 v8, 1, v163
	v_xor_b32_e32 v9, 2, v163
	v_xor_b32_e32 v10, 4, v163
	v_xor_b32_e32 v11, 8, v163
	v_xor_b32_e32 v12, 16, v163
	v_xor_b32_e32 v13, 32, v163
	v_lshlrev_b32_e32 v8, 2, v8
	v_lshlrev_b32_e32 v9, 2, v9
	v_lshlrev_b32_e32 v10, 2, v10
	v_lshlrev_b32_e32 v11, 2, v11
	v_lshlrev_b32_e32 v12, 2, v12
	v_lshlrev_b32_e32 v13, 2, v13
	s_lshl_b32 s62, s94, 12
	s_lshl_b32 s63, s94, 13
	s_mov_b64 s[92:93], 0x1000
	v_mov_b32_e32 v237, 0
	v_mov_b32_e32 v236, v5
	v_lshl_add_u64 v[236:237], v[0:1], 0, v[236:237]
	global_load_dwordx4 v[16:19], v[236:237], off offset:0
	global_load_dwordx4 v[20:23], v[236:237], off offset:16
	global_load_dwordx4 v[24:27], v[236:237], off offset:2048
	global_load_dwordx4 v[28:31], v[236:237], off offset:2064
	v_lshl_add_u64 v[236:237], v[236:237], 0, s[92:93]
	global_load_dwordx4 v[32:35], v[236:237], off offset:0
	global_load_dwordx4 v[36:39], v[236:237], off offset:16
	global_load_dwordx4 v[40:43], v[236:237], off offset:2048
	global_load_dwordx4 v[44:47], v[236:237], off offset:2064
	v_mov_b32_e32 v237, 0
	v_mov_b32_e32 v236, v5
	v_lshl_add_u64 v[236:237], v[2:3], 0, v[236:237]
	global_load_dwordx4 v[48:51], v[236:237], off offset:0
	global_load_dwordx4 v[52:55], v[236:237], off offset:16
	global_load_dwordx4 v[56:59], v[236:237], off offset:2048
	global_load_dwordx4 v[60:63], v[236:237], off offset:2064
	v_lshl_add_u64 v[236:237], v[236:237], 0, s[92:93]
	global_load_dwordx4 v[64:67], v[236:237], off offset:0
	global_load_dwordx4 v[68:71], v[236:237], off offset:16
	global_load_dwordx4 v[72:75], v[236:237], off offset:2048
	global_load_dwordx4 v[76:79], v[236:237], off offset:2064
	s_add_u32 s24, s28, 0x2a000000
	s_addc_u32 s25, s29, 0
	s_lshl_b32 s92, s32, 12
	s_add_u32 s24, s24, s92
	s_addc_u32 s25, s25, 0
	s_add_u32 s26, s28, 0x36000000
	s_addc_u32 s27, s29, 0
	s_lshl_b32 s92, s32, 12
	s_add_u32 s26, s26, s92
	s_addc_u32 s27, s27, 0
	s_add_u32 s70, s28, 0x36000000
	s_addc_u32 s71, s29, 0
	s_lshl_b32 s92, s32, 12
	s_add_u32 s70, s70, s92
	s_addc_u32 s71, s71, 0
	s_add_u32 s78, s28, 0xe000000
	s_addc_u32 s79, s29, 0
	s_lshl_b32 s92, s32, 12
	s_add_u32 s78, s78, s92
	s_addc_u32 s79, s79, 0
	global_load_dwordx4 v[80:83], v5, s[24:25] offset:0 nt
	global_load_dwordx4 v[84:87], v5, s[24:25] offset:1024 nt
	global_load_dwordx4 v[88:91], v5, s[24:25] offset:2048 nt
	global_load_dwordx4 v[92:95], v5, s[24:25] offset:3072 nt
	global_load_dwordx4 v[112:115], v5, s[26:27] offset:0 nt
	global_load_dwordx4 v[116:119], v5, s[26:27] offset:1024 nt
	global_load_dwordx4 v[120:123], v5, s[26:27] offset:2048 nt
	global_load_dwordx4 v[124:127], v5, s[26:27] offset:3072 nt
	s_add_u32 s24, s24, s62
	s_addc_u32 s25, s25, 0
	s_add_u32 s26, s26, s62
	s_addc_u32 s27, s27, 0
	s_add_u32 s84, s32, s94
	s_cmp_lt_u32 s84, 0x8000
	s_cbranch_scc0 .Lrow_rp2_first_last
	global_load_dwordx4 v[96:99], v5, s[24:25] offset:0 nt
	global_load_dwordx4 v[100:103], v5, s[24:25] offset:1024 nt
	global_load_dwordx4 v[104:107], v5, s[24:25] offset:2048 nt
	global_load_dwordx4 v[108:111], v5, s[24:25] offset:3072 nt
	global_load_dwordx4 v[132:135], v5, s[26:27] offset:0 nt
	global_load_dwordx4 v[136:139], v5, s[26:27] offset:1024 nt
	global_load_dwordx4 v[140:143], v5, s[26:27] offset:2048 nt
	global_load_dwordx4 v[144:147], v5, s[26:27] offset:3072 nt
	s_add_u32 s24, s24, s62
	s_addc_u32 s25, s25, 0
	s_add_u32 s26, s26, s62
	s_addc_u32 s27, s27, 0
	s_waitcnt vmcnt(8)
	s_branch .Lrow_rp2_compA

; #define NTL(p) __builtin_nontemporal_load(&(p))
; __device__ __forceinline__ float bf_lo(unsigned u) { return __uint_as_float(u << 16); }
; __device__ __forceinline__ float bf_hi(unsigned u) { return __uint_as_float(u & 0xffff0000u); }
; template <bool HAS_H, bool XIN_BF, bool XOUT_BF>
; __device__ __forceinline__ void row_pass(const bf16_t* y, const void* xin, void* xout, const float* g_post, const float* g_pre, bf16_t* hout, int G, int blk) {
;     ...
;     for (int row = gw; row < MT; row += NGW) {
;         const u32x2* yr = (const u32x2*)(y + (size_t)row * DM) + lane;
;         const f32x4* xr = (const f32x4*)((const float*)xin + (size_t)row * DM) + lane;
;         const u32x2* xrb = (const u32x2*)((const bf16_t*)xin + (size_t)row * DM) + lane;
;         f32x4 yv[8], xv[8]; float s = 0.f;
; #pragma unroll
;         for (int j = 0; j < 8; ++j) { const u32x2 w = NTL(yr[64 * j]); yv[j] = (f32x4){bf_lo(w.x), bf_hi(w.x), bf_lo(w.y), bf_hi(w.y)};
;             if (XIN_BF) { const u32x2 xw = NTL(xrb[64 * j]); xv[j] = (f32x4){bf_lo(xw.x), bf_hi(xw.x), bf_lo(xw.y), bf_hi(xw.y)}; } else xv[j] = NTL(xr[64 * j]);
.Lrow_rp2_top:
	s_add_u32 s84, s32, s94
	s_cmp_lt_u32 s84, 0x8000
	s_cbranch_scc0 .Lrow_rp2_lastA
	global_load_dwordx4 v[96:99], v5, s[24:25] offset:0 nt
	global_load_dwordx4 v[100:103], v5, s[24:25] offset:1024 nt
	global_load_dwordx4 v[104:107], v5, s[24:25] offset:2048 nt
	global_load_dwordx4 v[108:111], v5, s[24:25] offset:3072 nt
	global_load_dwordx4 v[132:135], v5, s[26:27] offset:0 nt
	global_load_dwordx4 v[136:139], v5, s[26:27] offset:1024 nt
	global_load_dwordx4 v[140:143], v5, s[26:27] offset:2048 nt
	global_load_dwordx4 v[144:147], v5, s[26:27] offset:3072 nt
	s_add_u32 s24, s24, s62
	s_addc_u32 s25, s25, 0
	s_add_u32 s26, s26, s62
	s_addc_u32 s27, s27, 0
	s_waitcnt vmcnt(16)
	s_branch .Lrow_rp2_compA

; __device__ __forceinline__ unsigned cvtpk(float lo, float hi) { f32x2_t v = {lo, hi}; bf16x2_t b = __builtin_convertvector(v, bf16x2_t); return __builtin_bit_cast(unsigned, b); }
; #define NTL(p) __builtin_nontemporal_load(&(p))
; #define NTS(v, p) __builtin_nontemporal_store((v), &(p))
; __device__ __forceinline__ float bf_lo(unsigned u) { return __uint_as_float(u << 16); }
; __device__ __forceinline__ float bf_hi(unsigned u) { return __uint_as_float(u & 0xffff0000u); }
; template <bool HAS_H, bool XIN_BF, bool XOUT_BF>
; __device__ __forceinline__ void row_pass(const bf16_t* y, const void* xin, void* xout, const float* g_post, const float* g_pre, bf16_t* hout, int G, int blk) {
;     ...
;         f32x4 yv[8], xv[8]; float s = 0.f;
; #pragma unroll
;         for (int j = 0; j < 8; ++j) { const u32x2 w = NTL(yr[64 * j]); yv[j] = (f32x4){bf_lo(w.x), bf_hi(w.x), bf_lo(w.y), bf_hi(w.y)};
;             if (XIN_BF) { const u32x2 xw = NTL(xrb[64 * j]); xv[j] = (f32x4){bf_lo(xw.x), bf_hi(xw.x), bf_lo(xw.y), bf_hi(xw.y)}; } else xv[j] = NTL(xr[64 * j]);
;             s += (yv[j].x * yv[j].x + yv[j].y * yv[j].y) + (yv[j].z * yv[j].z + yv[j].w * yv[j].w); }
;         const float r = 1.0f / sqrtf(wave_sum(s) * (1.0f / DM) + EPS);
;         const f32x4* gp = (const f32x4*)g_post + lane;
;         f32x4* xo = (f32x4*)((float*)xout + (size_t)row * DM) + lane;
;         u32x2* xob = (u32x2*)((bf16_t*)xout + (size_t)row * DM) + lane;
;         float s1 = 0.f;
; #pragma unroll
;         for (int j = 0; j < 8; ++j) { const f32x4 gv = gp[64 * j]; xv[j] = xv[j] + yv[j] * r * gv;
;             if (XOUT_BF) { u32x2 w; w.x = cvtpk(xv[j].x, xv[j].y); w.y = cvtpk(xv[j].z, xv[j].w); NTS(w, xob[64 * j]); } else NTS(xv[j], xo[64 * j]);
.Lrow_rp2_compA:
	v_lshlrev_b32_e32 v148, 16, v112
	v_and_b32_e32 v149, 0xffff0000, v112
	v_lshlrev_b32_e32 v150, 16, v113
	v_and_b32_e32 v151, 0xffff0000, v113
	v_lshlrev_b32_e32 v152, 16, v114
	v_and_b32_e32 v153, 0xffff0000, v114
	v_lshlrev_b32_e32 v154, 16, v115
	v_and_b32_e32 v155, 0xffff0000, v115
	v_lshlrev_b32_e32 v156, 16, v116
	v_and_b32_e32 v157, 0xffff0000, v116
	v_lshlrev_b32_e32 v158, 16, v117
	v_and_b32_e32 v159, 0xffff0000, v117
	v_lshlrev_b32_e32 v164, 16, v118
	v_and_b32_e32 v165, 0xffff0000, v118
	v_lshlrev_b32_e32 v166, 16, v119
	v_and_b32_e32 v167, 0xffff0000, v119
	v_lshlrev_b32_e32 v168, 16, v120
	v_and_b32_e32 v169, 0xffff0000, v120
	v_lshlrev_b32_e32 v170, 16, v121
	v_and_b32_e32 v171, 0xffff0000, v121
	v_lshlrev_b32_e32 v172, 16, v122
	v_and_b32_e32 v173, 0xffff0000, v122
	v_lshlrev_b32_e32 v174, 16, v123
	v_and_b32_e32 v175, 0xffff0000, v123
	v_lshlrev_b32_e32 v176, 16, v124
	v_and_b32_e32 v177, 0xffff0000, v124
	v_lshlrev_b32_e32 v178, 16, v125
	v_and_b32_e32 v179, 0xffff0000, v125
	v_lshlrev_b32_e32 v180, 16, v126
	v_and_b32_e32 v181, 0xffff0000, v126
	v_lshlrev_b32_e32 v182, 16, v127
	v_and_b32_e32 v183, 0xffff0000, v127
	v_lshlrev_b32_e32 v184, 16, v80
	v_and_b32_e32 v185, 0xffff0000, v80
	v_lshlrev_b32_e32 v186, 16, v81
	v_and_b32_e32 v187, 0xffff0000, v81
	v_lshlrev_b32_e32 v192, 16, v82
	v_and_b32_e32 v193, 0xffff0000, v82
	v_lshlrev_b32_e32 v194, 16, v83
	v_and_b32_e32 v195, 0xffff0000, v83
	v_lshlrev_b32_e32 v196, 16, v84
	v_and_b32_e32 v197, 0xffff0000, v84
	v_lshlrev_b32_e32 v198, 16, v85
	v_and_b32_e32 v199, 0xffff0000, v85
	v_lshlrev_b32_e32 v200, 16, v86
	v_and_b32_e32 v201, 0xffff0000, v86
	v_lshlrev_b32_e32 v202, 16, v87
	v_and_b32_e32 v203, 0xffff0000, v87
	v_lshlrev_b32_e32 v204, 16, v88
	v_and_b32_e32 v205, 0xffff0000, v88
	v_lshlrev_b32_e32 v206, 16, v89
	v_and_b32_e32 v207, 0xffff0000, v89
	v_lshlrev_b32_e32 v208, 16, v90
	v_and_b32_e32 v209, 0xffff0000, v90
	v_lshlrev_b32_e32 v210, 16, v91
	v_and_b32_e32 v211, 0xffff0000, v91
	v_lshlrev_b32_e32 v212, 16, v92
	v_and_b32_e32 v213, 0xffff0000, v92
	v_lshlrev_b32_e32 v214, 16, v93
	v_and_b32_e32 v215, 0xffff0000, v93
	v_lshlrev_b32_e32 v216, 16, v94
	v_and_b32_e32 v217, 0xffff0000, v94
	v_lshlrev_b32_e32 v218, 16, v95
	v_and_b32_e32 v219, 0xffff0000, v95
	v_pk_mul_f32 v[14:15], v[184:185], v[184:185]
	v_pk_mul_f32 v[130:131], v[186:187], v[186:187]
	v_pk_fma_f32 v[14:15], v[192:193], v[192:193], v[14:15]
	v_pk_fma_f32 v[130:131], v[194:195], v[194:195], v[130:131]
	v_pk_fma_f32 v[14:15], v[196:197], v[196:197], v[14:15]
	v_pk_fma_f32 v[130:131], v[198:199], v[198:199], v[130:131]
	v_pk_fma_f32 v[14:15], v[200:201], v[200:201], v[14:15]
	v_pk_fma_f32 v[130:131], v[202:203], v[202:203], v[130:131]
	v_pk_fma_f32 v[14:15], v[204:205], v[204:205], v[14:15]
	v_pk_fma_f32 v[130:131], v[206:207], v[206:207], v[130:131]
	v_pk_fma_f32 v[14:15], v[208:209], v[208:209], v[14:15]
	v_pk_fma_f32 v[130:131], v[210:211], v[210:211], v[130:131]
	v_pk_fma_f32 v[14:15], v[212:213], v[212:213], v[14:15]
	v_pk_fma_f32 v[130:131], v[214:215], v[214:215], v[130:131]
	v_pk_fma_f32 v[14:15], v[216:217], v[216:217], v[14:15]
	v_pk_fma_f32 v[130:131], v[218:219], v[218:219], v[130:131]
	v_pk_add_f32 v[14:15], v[14:15], v[130:131]
	s_nop 0
	v_add_f32_e32 v161, v14, v15
	ds_bpermute_b32 v188, v8, v161
	s_waitcnt lgkmcnt(0)
	v_add_f32_e32 v161, v161, v188
	ds_bpermute_b32 v188, v9, v161
	s_waitcnt lgkmcnt(0)
	v_add_f32_e32 v161, v161, v188
	ds_bpermute_b32 v188, v10, v161
	s_waitcnt lgkmcnt(0)
	v_add_f32_e32 v161, v161, v188
	ds_bpermute_b32 v188, v11, v161
	s_waitcnt lgkmcnt(0)
	v_add_f32_e32 v161, v161, v188
	ds_bpermute_b32 v188, v12, v161
	s_waitcnt lgkmcnt(0)
	v_add_f32_e32 v161, v161, v188
	ds_bpermute_b32 v188, v13, v161
	s_waitcnt lgkmcnt(0)
	v_add_f32_e32 v161, v161, v188
	v_fmamk_f32 v161, v161, 0x3a000000, v6
	v_mul_f32_e32 v189, 0x4f800000, v161
	v_cmp_gt_f32_e32 vcc, s85, v161
	s_nop 1
	v_cndmask_b32_e32 v161, v161, v189, vcc
	v_sqrt_f32_e32 v189, v161
	s_nop 0
	v_add_u32_e32 v191, -1, v189
	v_add_u32_e32 v226, 1, v189
	v_fma_f32 v227, -v191, v189, v161
	v_fma_f32 v188, -v226, v189, v161
	v_cmp_ge_f32_e64 s[80:81], 0, v227
	s_nop 1
	v_cndmask_b32_e64 v189, v189, v191, s[80:81]
	v_cmp_lt_f32_e64 s[80:81], 0, v188
	s_nop 1
	v_cndmask_b32_e64 v189, v189, v226, s[80:81]
	v_mul_f32_e32 v191, 0x37800000, v189
	v_cndmask_b32_e32 v189, v189, v191, vcc
	v_cmp_class_f32_e32 vcc, v161, v7
	s_nop 1
	v_cndmask_b32_e32 v161, v189, v161, vcc
	v_div_scale_f32 v189, s[80:81], v161, v161, 1.0
	v_rcp_f32_e32 v226, v189
	v_div_scale_f32 v191, vcc, 1.0, v161, 1.0
	v_fma_f32 v227, -v189, v226, 1.0
	v_fmac_f32_e32 v226, v227, v226
	v_mul_f32_e32 v227, v191, v226
	v_fma_f32 v188, -v189, v227, v191
	v_fmac_f32_e32 v227, v188, v226
	v_fma_f32 v189, -v189, v227, v191
	v_div_fmas_f32 v189, v189, v226, v227
	v_div_fixup_f32 v220, v189, v161, 1.0
	v_pk_mul_f32 v[222:223], v[184:185], v[220:221] op_sel_hi:[1,0]
	v_pk_mul_f32 v[224:225], v[186:187], v[220:221] op_sel_hi:[1,0]
	v_pk_fma_f32 v[148:149], v[16:17], v[222:223], v[148:149]
	v_pk_fma_f32 v[150:151], v[18:19], v[224:225], v[150:151]
	v_cvt_pk_bf16_f32 v228, v148, v149
	v_cvt_pk_bf16_f32 v229, v150, v151
	v_pk_mul_f32 v[222:223], v[192:193], v[220:221] op_sel_hi:[1,0]
	v_pk_mul_f32 v[224:225], v[194:195], v[220:221] op_sel_hi:[1,0]
	v_pk_fma_f32 v[152:153], v[20:21], v[222:223], v[152:153]
	v_pk_fma_f32 v[154:155], v[22:23], v[224:225], v[154:155]
	v_cvt_pk_bf16_f32 v230, v152, v153
	v_cvt_pk_bf16_f32 v231, v154, v155
	global_store_dwordx4 v5, v[228:231], s[70:71] offset:0 nt
	v_pk_mul_f32 v[222:223], v[196:197], v[220:221] op_sel_hi:[1,0]
; __device__ __forceinline__ unsigned cvtpk(float lo, float hi) { f32x2_t v = {lo, hi}; bf16x2_t b = __builtin_convertvector(v, bf16x2_t); return __builtin_bit_cast(unsigned, b); }
; #define NTS(v, p) __builtin_nontemporal_store((v), &(p))
; template <bool HAS_H, bool XIN_BF, bool XOUT_BF>
; __device__ __forceinline__ void row_pass(const bf16_t* y, const void* xin, void* xout, const float* g_post, const float* g_pre, bf16_t* hout, int G, int blk) {
;     ...
;         for (int j = 0; j < 8; ++j) { const f32x4 gv = gp[64 * j]; xv[j] = xv[j] + yv[j] * r * gv;
;             if (XOUT_BF) { u32x2 w; w.x = cvtpk(xv[j].x, xv[j].y); w.y = cvtpk(xv[j].z, xv[j].w); NTS(w, xob[64 * j]); } else NTS(xv[j], xo[64 * j]);
;             s1 += (xv[j].x * xv[j].x + xv[j].y * xv[j].y) + (xv[j].z * xv[j].z + xv[j].w * xv[j].w); }
;         if (HAS_H) {
;             const float r1 = 1.0f / sqrtf(wave_sum(s1) * (1.0f / DM) + EPS);
	v_pk_mul_f32 v[224:225], v[198:199], v[220:221] op_sel_hi:[1,0]
	v_pk_fma_f32 v[156:157], v[24:25], v[222:223], v[156:157]
	v_pk_fma_f32 v[158:159], v[26:27], v[224:225], v[158:159]
	v_cvt_pk_bf16_f32 v232, v156, v157
	v_cvt_pk_bf16_f32 v233, v158, v159
	v_pk_mul_f32 v[222:223], v[200:201], v[220:221] op_sel_hi:[1,0]
	v_pk_mul_f32 v[224:225], v[202:203], v[220:221] op_sel_hi:[1,0]
	v_pk_fma_f32 v[164:165], v[28:29], v[222:223], v[164:165]
	v_pk_fma_f32 v[166:167], v[30:31], v[224:225], v[166:167]
	v_cvt_pk_bf16_f32 v234, v164, v165
	v_cvt_pk_bf16_f32 v235, v166, v167
	global_store_dwordx4 v5, v[232:235], s[70:71] offset:1024 nt
	v_pk_mul_f32 v[222:223], v[204:205], v[220:221] op_sel_hi:[1,0]
	v_pk_mul_f32 v[224:225], v[206:207], v[220:221] op_sel_hi:[1,0]
	v_pk_fma_f32 v[168:169], v[32:33], v[222:223], v[168:169]
	v_pk_fma_f32 v[170:171], v[34:35], v[224:225], v[170:171]
	v_cvt_pk_bf16_f32 v228, v168, v169
	v_cvt_pk_bf16_f32 v229, v170, v171
	v_pk_mul_f32 v[222:223], v[208:209], v[220:221] op_sel_hi:[1,0]
	v_pk_mul_f32 v[224:225], v[210:211], v[220:221] op_sel_hi:[1,0]
	v_pk_fma_f32 v[172:173], v[36:37], v[222:223], v[172:173]
	v_pk_fma_f32 v[174:175], v[38:39], v[224:225], v[174:175]
	v_cvt_pk_bf16_f32 v230, v172, v173
	v_cvt_pk_bf16_f32 v231, v174, v175
	global_store_dwordx4 v5, v[228:231], s[70:71] offset:2048 nt
	v_pk_mul_f32 v[222:223], v[212:213], v[220:221] op_sel_hi:[1,0]
	v_pk_mul_f32 v[224:225], v[214:215], v[220:221] op_sel_hi:[1,0]
	v_pk_fma_f32 v[176:177], v[40:41], v[222:223], v[176:177]
	v_pk_fma_f32 v[178:179], v[42:43], v[224:225], v[178:179]
	v_cvt_pk_bf16_f32 v232, v176, v177
	v_cvt_pk_bf16_f32 v233, v178, v179
	v_pk_mul_f32 v[222:223], v[216:217], v[220:221] op_sel_hi:[1,0]
	v_pk_mul_f32 v[224:225], v[218:219], v[220:221] op_sel_hi:[1,0]
	v_pk_fma_f32 v[180:181], v[44:45], v[222:223], v[180:181]
	v_pk_fma_f32 v[182:183], v[46:47], v[224:225], v[182:183]
	v_cvt_pk_bf16_f32 v234, v180, v181
	v_cvt_pk_bf16_f32 v235, v182, v183
	global_store_dwordx4 v5, v[232:235], s[70:71] offset:3072 nt
	s_add_u32 s70, s70, s62
	s_addc_u32 s71, s71, 0
	v_pk_mul_f32 v[14:15], v[148:149], v[148:149]
	v_pk_mul_f32 v[130:131], v[150:151], v[150:151]
	v_pk_fma_f32 v[14:15], v[152:153], v[152:153], v[14:15]
	v_pk_fma_f32 v[130:131], v[154:155], v[154:155], v[130:131]
	v_pk_fma_f32 v[14:15], v[156:157], v[156:157], v[14:15]
	v_pk_fma_f32 v[130:131], v[158:159], v[158:159], v[130:131]
	v_pk_fma_f32 v[14:15], v[164:165], v[164:165], v[14:15]
	v_pk_fma_f32 v[130:131], v[166:167], v[166:167], v[130:131]
	v_pk_fma_f32 v[14:15], v[168:169], v[168:169], v[14:15]
	v_pk_fma_f32 v[130:131], v[170:171], v[170:171], v[130:131]
	v_pk_fma_f32 v[14:15], v[172:173], v[172:173], v[14:15]
	v_pk_fma_f32 v[130:131], v[174:175], v[174:175], v[130:131]
	v_pk_fma_f32 v[14:15], v[176:177], v[176:177], v[14:15]
	v_pk_fma_f32 v[130:131], v[178:179], v[178:179], v[130:131]
	v_pk_fma_f32 v[14:15], v[180:181], v[180:181], v[14:15]
	v_pk_fma_f32 v[130:131], v[182:183], v[182:183], v[130:131]
	v_pk_add_f32 v[14:15], v[14:15], v[130:131]
	s_nop 0
	v_add_f32_e32 v161, v14, v15
	ds_bpermute_b32 v188, v8, v161
	s_waitcnt lgkmcnt(0)
	v_add_f32_e32 v161, v161, v188
	ds_bpermute_b32 v188, v9, v161
	s_waitcnt lgkmcnt(0)
	v_add_f32_e32 v161, v161, v188
	ds_bpermute_b32 v188, v10, v161
	s_waitcnt lgkmcnt(0)
	v_add_f32_e32 v161, v161, v188
	ds_bpermute_b32 v188, v11, v161
	s_waitcnt lgkmcnt(0)
	v_add_f32_e32 v161, v161, v188
	ds_bpermute_b32 v188, v12, v161
	s_waitcnt lgkmcnt(0)
	v_add_f32_e32 v161, v161, v188
	ds_bpermute_b32 v188, v13, v161
	s_waitcnt lgkmcnt(0)
; __device__ __forceinline__ unsigned cvtpk(float lo, float hi) { f32x2_t v = {lo, hi}; bf16x2_t b = __builtin_convertvector(v, bf16x2_t); return __builtin_bit_cast(unsigned, b); }
; #define NTL(p) __builtin_nontemporal_load(&(p))
; __device__ __forceinline__ float bf_lo(unsigned u) { return __uint_as_float(u << 16); }
; __device__ __forceinline__ float bf_hi(unsigned u) { return __uint_as_float(u & 0xffff0000u); }
; template <bool HAS_H, bool XIN_BF, bool XOUT_BF>
; __device__ __forceinline__ void row_pass(const bf16_t* y, const void* xin, void* xout, const float* g_post, const float* g_pre, bf16_t* hout, int G, int blk) {
;     ...
;     for (int row = gw; row < MT; row += NGW) {
;         const u32x2* yr = (const u32x2*)(y + (size_t)row * DM) + lane;
;         const f32x4* xr = (const f32x4*)((const float*)xin + (size_t)row * DM) + lane;
;         const u32x2* xrb = (const u32x2*)((const bf16_t*)xin + (size_t)row * DM) + lane;
;         f32x4 yv[8], xv[8]; float s = 0.f;
; #pragma unroll
;         for (int j = 0; j < 8; ++j) { const u32x2 w = NTL(yr[64 * j]); yv[j] = (f32x4){bf_lo(w.x), bf_hi(w.x), bf_lo(w.y), bf_hi(w.y)};
;             if (XIN_BF) { const u32x2 xw = NTL(xrb[64 * j]); xv[j] = (f32x4){bf_lo(xw.x), bf_hi(xw.x), bf_lo(xw.y), bf_hi(xw.y)}; } else xv[j] = NTL(xr[64 * j]);
;     ...
;             const float r1 = 1.0f / sqrtf(wave_sum(s1) * (1.0f / DM) + EPS);
;             const f32x4* gq = (const f32x4*)g_pre + lane;
;             u32x2* ho = (u32x2*)(hout + (size_t)row * DM) + lane;
; #pragma unroll
;             for (int j = 0; j < 8; ++j) { const f32x4 gv = gq[64 * j]; u32x2 w; w.x = cvtpk(xv[j].x * r1 * gv.x, xv[j].y * r1 * gv.y); w.y = cvtpk(xv[j].z * r1 * gv.z, xv[j].w * r1 * gv.w); ho[64 * j] = w; }
	v_add_f32_e32 v161, v161, v188
	v_fmamk_f32 v161, v161, 0x3a000000, v6
	v_mul_f32_e32 v189, 0x4f800000, v161
	v_cmp_gt_f32_e32 vcc, s85, v161
	s_nop 1
	v_cndmask_b32_e32 v161, v161, v189, vcc
	v_sqrt_f32_e32 v189, v161
	s_nop 0
	v_add_u32_e32 v191, -1, v189
	v_add_u32_e32 v226, 1, v189
	v_fma_f32 v227, -v191, v189, v161
	v_fma_f32 v188, -v226, v189, v161
	v_cmp_ge_f32_e64 s[80:81], 0, v227
	s_nop 1
	v_cndmask_b32_e64 v189, v189, v191, s[80:81]
	v_cmp_lt_f32_e64 s[80:81], 0, v188
	s_nop 1
	v_cndmask_b32_e64 v189, v189, v226, s[80:81]
	v_mul_f32_e32 v191, 0x37800000, v189
	v_cndmask_b32_e32 v189, v189, v191, vcc
	v_cmp_class_f32_e32 vcc, v161, v7
	s_nop 1
	v_cndmask_b32_e32 v161, v189, v161, vcc
	v_div_scale_f32 v189, s[80:81], v161, v161, 1.0
	v_rcp_f32_e32 v226, v189
	v_div_scale_f32 v191, vcc, 1.0, v161, 1.0
	v_fma_f32 v227, -v189, v226, 1.0
	v_fmac_f32_e32 v226, v227, v226
	v_mul_f32_e32 v227, v191, v226
	v_fma_f32 v188, -v189, v227, v191
	v_fmac_f32_e32 v227, v188, v226
	v_fma_f32 v189, -v189, v227, v191
	v_div_fmas_f32 v189, v189, v226, v227
	v_div_fixup_f32 v220, v189, v161, 1.0
	v_pk_mul_f32 v[222:223], v[148:149], v[220:221] op_sel_hi:[1,0]
	v_pk_mul_f32 v[224:225], v[150:151], v[220:221] op_sel_hi:[1,0]
	v_pk_mul_f32 v[222:223], v[48:49], v[222:223]
	v_pk_mul_f32 v[224:225], v[50:51], v[224:225]
	v_cvt_pk_bf16_f32 v228, v222, v223
	v_cvt_pk_bf16_f32 v229, v224, v225
	v_pk_mul_f32 v[222:223], v[152:153], v[220:221] op_sel_hi:[1,0]
	v_pk_mul_f32 v[224:225], v[154:155], v[220:221] op_sel_hi:[1,0]
	v_pk_mul_f32 v[222:223], v[52:53], v[222:223]
	v_pk_mul_f32 v[224:225], v[54:55], v[224:225]
	v_cvt_pk_bf16_f32 v230, v222, v223
	v_cvt_pk_bf16_f32 v231, v224, v225
	global_store_dwordx4 v5, v[228:231], s[78:79] offset:0
	v_pk_mul_f32 v[222:223], v[156:157], v[220:221] op_sel_hi:[1,0]
	v_pk_mul_f32 v[224:225], v[158:159], v[220:221] op_sel_hi:[1,0]
	v_pk_mul_f32 v[222:223], v[56:57], v[222:223]
	v_pk_mul_f32 v[224:225], v[58:59], v[224:225]
	v_cvt_pk_bf16_f32 v232, v222, v223
	v_cvt_pk_bf16_f32 v233, v224, v225
	v_pk_mul_f32 v[222:223], v[164:165], v[220:221] op_sel_hi:[1,0]
	v_pk_mul_f32 v[224:225], v[166:167], v[220:221] op_sel_hi:[1,0]
	v_pk_mul_f32 v[222:223], v[60:61], v[222:223]
	v_pk_mul_f32 v[224:225], v[62:63], v[224:225]
	v_cvt_pk_bf16_f32 v234, v222, v223
	v_cvt_pk_bf16_f32 v235, v224, v225
	global_store_dwordx4 v5, v[232:235], s[78:79] offset:1024
	v_pk_mul_f32 v[222:223], v[168:169], v[220:221] op_sel_hi:[1,0]
	v_pk_mul_f32 v[224:225], v[170:171], v[220:221] op_sel_hi:[1,0]
	v_pk_mul_f32 v[222:223], v[64:65], v[222:223]
	v_pk_mul_f32 v[224:225], v[66:67], v[224:225]
	v_cvt_pk_bf16_f32 v228, v222, v223
	v_cvt_pk_bf16_f32 v229, v224, v225
	v_pk_mul_f32 v[222:223], v[172:173], v[220:221] op_sel_hi:[1,0]
	v_pk_mul_f32 v[224:225], v[174:175], v[220:221] op_sel_hi:[1,0]
	v_pk_mul_f32 v[222:223], v[68:69], v[222:223]
	v_pk_mul_f32 v[224:225], v[70:71], v[224:225]
	v_cvt_pk_bf16_f32 v230, v222, v223
	v_cvt_pk_bf16_f32 v231, v224, v225
	global_store_dwordx4 v5, v[228:231], s[78:79] offset:2048
	v_pk_mul_f32 v[222:223], v[176:177], v[220:221] op_sel_hi:[1,0]
	v_pk_mul_f32 v[224:225], v[178:179], v[220:221] op_sel_hi:[1,0]
	v_pk_mul_f32 v[222:223], v[72:73], v[222:223]
	v_pk_mul_f32 v[224:225], v[74:75], v[224:225]
	v_cvt_pk_bf16_f32 v232, v222, v223
	v_cvt_pk_bf16_f32 v233, v224, v225
	v_pk_mul_f32 v[222:223], v[180:181], v[220:221] op_sel_hi:[1,0]
	v_pk_mul_f32 v[224:225], v[182:183], v[220:221] op_sel_hi:[1,0]
	v_pk_mul_f32 v[222:223], v[76:77], v[222:223]
	v_pk_mul_f32 v[224:225], v[78:79], v[224:225]
	v_cvt_pk_bf16_f32 v234, v222, v223
	v_cvt_pk_bf16_f32 v235, v224, v225
	global_store_dwordx4 v5, v[232:235], s[78:79] offset:3072
	s_add_u32 s78, s78, s62
	s_addc_u32 s79, s79, 0
	s_mov_b32 s32, s84
	s_cmp_lt_u32 s32, 0x8000
	s_cbranch_scc0 .Lrow_rp2_done
	s_add_u32 s84, s32, s94
	s_cmp_lt_u32 s84, 0x8000
	s_cbranch_scc0 .Lrow_rp2_lastB
	global_load_dwordx4 v[80:83], v5, s[24:25] offset:0 nt
	global_load_dwordx4 v[84:87], v5, s[24:25] offset:1024 nt
	global_load_dwordx4 v[88:91], v5, s[24:25] offset:2048 nt
	global_load_dwordx4 v[92:95], v5, s[24:25] offset:3072 nt
	global_load_dwordx4 v[112:115], v5, s[26:27] offset:0 nt
	global_load_dwordx4 v[116:119], v5, s[26:27] offset:1024 nt
	global_load_dwordx4 v[120:123], v5, s[26:27] offset:2048 nt
	global_load_dwordx4 v[124:127], v5, s[26:27] offset:3072 nt
	s_add_u32 s24, s24, s62
	s_addc_u32 s25, s25, 0
	s_add_u32 s26, s26, s62
	s_addc_u32 s27, s27, 0
	s_waitcnt vmcnt(16)
	s_branch .Lrow_rp2_compB

; __device__ __forceinline__ unsigned cvtpk(float lo, float hi) { f32x2_t v = {lo, hi}; bf16x2_t b = __builtin_convertvector(v, bf16x2_t); return __builtin_bit_cast(unsigned, b); }
; #define NTL(p) __builtin_nontemporal_load(&(p))
; #define NTS(v, p) __builtin_nontemporal_store((v), &(p))
; __device__ __forceinline__ float bf_lo(unsigned u) { return __uint_as_float(u << 16); }
; __device__ __forceinline__ float bf_hi(unsigned u) { return __uint_as_float(u & 0xffff0000u); }
; template <bool HAS_H, bool XIN_BF, bool XOUT_BF>
; __device__ __forceinline__ void row_pass(const bf16_t* y, const void* xin, void* xout, const float* g_post, const float* g_pre, bf16_t* hout, int G, int blk) {
;     ...
;         f32x4 yv[8], xv[8]; float s = 0.f;
; #pragma unroll
;         for (int j = 0; j < 8; ++j) { const u32x2 w = NTL(yr[64 * j]); yv[j] = (f32x4){bf_lo(w.x), bf_hi(w.x), bf_lo(w.y), bf_hi(w.y)};
;             if (XIN_BF) { const u32x2 xw = NTL(xrb[64 * j]); xv[j] = (f32x4){bf_lo(xw.x), bf_hi(xw.x), bf_lo(xw.y), bf_hi(xw.y)}; } else xv[j] = NTL(xr[64 * j]);
;             s += (yv[j].x * yv[j].x + yv[j].y * yv[j].y) + (yv[j].z * yv[j].z + yv[j].w * yv[j].w); }
;         const float r = 1.0f / sqrtf(wave_sum(s) * (1.0f / DM) + EPS);
;         const f32x4* gp = (const f32x4*)g_post + lane;
;         f32x4* xo = (f32x4*)((float*)xout + (size_t)row * DM) + lane;
;         u32x2* xob = (u32x2*)((bf16_t*)xout + (size_t)row * DM) + lane;
;         float s1 = 0.f;
; #pragma unroll
;         for (int j = 0; j < 8; ++j) { const f32x4 gv = gp[64 * j]; xv[j] = xv[j] + yv[j] * r * gv;
;             if (XOUT_BF) { u32x2 w; w.x = cvtpk(xv[j].x, xv[j].y); w.y = cvtpk(xv[j].z, xv[j].w); NTS(w, xob[64 * j]); } else NTS(xv[j], xo[64 * j]);
.Lrow_rp2_compB:
	v_lshlrev_b32_e32 v148, 16, v132
	v_and_b32_e32 v149, 0xffff0000, v132
	v_lshlrev_b32_e32 v150, 16, v133
	v_and_b32_e32 v151, 0xffff0000, v133
	v_lshlrev_b32_e32 v152, 16, v134
	v_and_b32_e32 v153, 0xffff0000, v134
	v_lshlrev_b32_e32 v154, 16, v135
	v_and_b32_e32 v155, 0xffff0000, v135
	v_lshlrev_b32_e32 v156, 16, v136
	v_and_b32_e32 v157, 0xffff0000, v136
	v_lshlrev_b32_e32 v158, 16, v137
	v_and_b32_e32 v159, 0xffff0000, v137
	v_lshlrev_b32_e32 v164, 16, v138
	v_and_b32_e32 v165, 0xffff0000, v138
	v_lshlrev_b32_e32 v166, 16, v139
	v_and_b32_e32 v167, 0xffff0000, v139
	v_lshlrev_b32_e32 v168, 16, v140
	v_and_b32_e32 v169, 0xffff0000, v140
	v_lshlrev_b32_e32 v170, 16, v141
	v_and_b32_e32 v171, 0xffff0000, v141
	v_lshlrev_b32_e32 v172, 16, v142
	v_and_b32_e32 v173, 0xffff0000, v142
	v_lshlrev_b32_e32 v174, 16, v143
	v_and_b32_e32 v175, 0xffff0000, v143
	v_lshlrev_b32_e32 v176, 16, v144
	v_and_b32_e32 v177, 0xffff0000, v144
	v_lshlrev_b32_e32 v178, 16, v145
	v_and_b32_e32 v179, 0xffff0000, v145
	v_lshlrev_b32_e32 v180, 16, v146
	v_and_b32_e32 v181, 0xffff0000, v146
	v_lshlrev_b32_e32 v182, 16, v147
	v_and_b32_e32 v183, 0xffff0000, v147
	v_lshlrev_b32_e32 v184, 16, v96
	v_and_b32_e32 v185, 0xffff0000, v96
	v_lshlrev_b32_e32 v186, 16, v97
	v_and_b32_e32 v187, 0xffff0000, v97
	v_lshlrev_b32_e32 v192, 16, v98
	v_and_b32_e32 v193, 0xffff0000, v98
	v_lshlrev_b32_e32 v194, 16, v99
	v_and_b32_e32 v195, 0xffff0000, v99
	v_lshlrev_b32_e32 v196, 16, v100
	v_and_b32_e32 v197, 0xffff0000, v100
	v_lshlrev_b32_e32 v198, 16, v101
	v_and_b32_e32 v199, 0xffff0000, v101
	v_lshlrev_b32_e32 v200, 16, v102
	v_and_b32_e32 v201, 0xffff0000, v102
	v_lshlrev_b32_e32 v202, 16, v103
	v_and_b32_e32 v203, 0xffff0000, v103
	v_lshlrev_b32_e32 v204, 16, v104
	v_and_b32_e32 v205, 0xffff0000, v104
	v_lshlrev_b32_e32 v206, 16, v105
	v_and_b32_e32 v207, 0xffff0000, v105
	v_lshlrev_b32_e32 v208, 16, v106
	v_and_b32_e32 v209, 0xffff0000, v106
	v_lshlrev_b32_e32 v210, 16, v107
	v_and_b32_e32 v211, 0xffff0000, v107
	v_lshlrev_b32_e32 v212, 16, v108
	v_and_b32_e32 v213, 0xffff0000, v108
	v_lshlrev_b32_e32 v214, 16, v109
	v_and_b32_e32 v215, 0xffff0000, v109
	v_lshlrev_b32_e32 v216, 16, v110
	v_and_b32_e32 v217, 0xffff0000, v110
	v_lshlrev_b32_e32 v218, 16, v111
	v_and_b32_e32 v219, 0xffff0000, v111
	v_pk_mul_f32 v[14:15], v[184:185], v[184:185]
	v_pk_mul_f32 v[130:131], v[186:187], v[186:187]
	v_pk_fma_f32 v[14:15], v[192:193], v[192:193], v[14:15]
	v_pk_fma_f32 v[130:131], v[194:195], v[194:195], v[130:131]
	v_pk_fma_f32 v[14:15], v[196:197], v[196:197], v[14:15]
	v_pk_fma_f32 v[130:131], v[198:199], v[198:199], v[130:131]
	v_pk_fma_f32 v[14:15], v[200:201], v[200:201], v[14:15]
	v_pk_fma_f32 v[130:131], v[202:203], v[202:203], v[130:131]
	v_pk_fma_f32 v[14:15], v[204:205], v[204:205], v[14:15]
	v_pk_fma_f32 v[130:131], v[206:207], v[206:207], v[130:131]
	v_pk_fma_f32 v[14:15], v[208:209], v[208:209], v[14:15]
	v_pk_fma_f32 v[130:131], v[210:211], v[210:211], v[130:131]
	v_pk_fma_f32 v[14:15], v[212:213], v[212:213], v[14:15]
	v_pk_fma_f32 v[130:131], v[214:215], v[214:215], v[130:131]
	v_pk_fma_f32 v[14:15], v[216:217], v[216:217], v[14:15]
	v_pk_fma_f32 v[130:131], v[218:219], v[218:219], v[130:131]
	v_pk_add_f32 v[14:15], v[14:15], v[130:131]
	s_nop 0
	v_add_f32_e32 v161, v14, v15
	ds_bpermute_b32 v188, v8, v161
	s_waitcnt lgkmcnt(0)
	v_add_f32_e32 v161, v161, v188
	ds_bpermute_b32 v188, v9, v161
	s_waitcnt lgkmcnt(0)
	v_add_f32_e32 v161, v161, v188
	ds_bpermute_b32 v188, v10, v161
	s_waitcnt lgkmcnt(0)
	v_add_f32_e32 v161, v161, v188
	ds_bpermute_b32 v188, v11, v161
	s_waitcnt lgkmcnt(0)
	v_add_f32_e32 v161, v161, v188
	ds_bpermute_b32 v188, v12, v161
	s_waitcnt lgkmcnt(0)
	v_add_f32_e32 v161, v161, v188
	ds_bpermute_b32 v188, v13, v161
	s_waitcnt lgkmcnt(0)
	v_add_f32_e32 v161, v161, v188
	v_fmamk_f32 v161, v161, 0x3a000000, v6
	v_mul_f32_e32 v189, 0x4f800000, v161
	v_cmp_gt_f32_e32 vcc, s85, v161
	s_nop 1
	v_cndmask_b32_e32 v161, v161, v189, vcc
	v_sqrt_f32_e32 v189, v161
	s_nop 0
	v_add_u32_e32 v191, -1, v189
	v_add_u32_e32 v226, 1, v189
	v_fma_f32 v227, -v191, v189, v161
	v_fma_f32 v188, -v226, v189, v161
	v_cmp_ge_f32_e64 s[80:81], 0, v227
	s_nop 1
	v_cndmask_b32_e64 v189, v189, v191, s[80:81]
	v_cmp_lt_f32_e64 s[80:81], 0, v188
	s_nop 1
	v_cndmask_b32_e64 v189, v189, v226, s[80:81]
	v_mul_f32_e32 v191, 0x37800000, v189
	v_cndmask_b32_e32 v189, v189, v191, vcc
	v_cmp_class_f32_e32 vcc, v161, v7
	s_nop 1
	v_cndmask_b32_e32 v161, v189, v161, vcc
	v_div_scale_f32 v189, s[80:81], v161, v161, 1.0
	v_rcp_f32_e32 v226, v189
	v_div_scale_f32 v191, vcc, 1.0, v161, 1.0
	v_fma_f32 v227, -v189, v226, 1.0
	v_fmac_f32_e32 v226, v227, v226
	v_mul_f32_e32 v227, v191, v226
	v_fma_f32 v188, -v189, v227, v191
	v_fmac_f32_e32 v227, v188, v226
	v_fma_f32 v189, -v189, v227, v191
	v_div_fmas_f32 v189, v189, v226, v227
	v_div_fixup_f32 v220, v189, v161, 1.0
	v_pk_mul_f32 v[222:223], v[184:185], v[220:221] op_sel_hi:[1,0]
	v_pk_mul_f32 v[224:225], v[186:187], v[220:221] op_sel_hi:[1,0]
	v_pk_fma_f32 v[148:149], v[16:17], v[222:223], v[148:149]
	v_pk_fma_f32 v[150:151], v[18:19], v[224:225], v[150:151]
	v_cvt_pk_bf16_f32 v228, v148, v149
	v_cvt_pk_bf16_f32 v229, v150, v151
	v_pk_mul_f32 v[222:223], v[192:193], v[220:221] op_sel_hi:[1,0]
	v_pk_mul_f32 v[224:225], v[194:195], v[220:221] op_sel_hi:[1,0]
	v_pk_fma_f32 v[152:153], v[20:21], v[222:223], v[152:153]
	v_pk_fma_f32 v[154:155], v[22:23], v[224:225], v[154:155]
	v_cvt_pk_bf16_f32 v230, v152, v153
	v_cvt_pk_bf16_f32 v231, v154, v155
	global_store_dwordx4 v5, v[228:231], s[70:71] offset:0 nt
; __device__ __forceinline__ unsigned cvtpk(float lo, float hi) { f32x2_t v = {lo, hi}; bf16x2_t b = __builtin_convertvector(v, bf16x2_t); return __builtin_bit_cast(unsigned, b); }
; #define NTS(v, p) __builtin_nontemporal_store((v), &(p))
; template <bool HAS_H, bool XIN_BF, bool XOUT_BF>
; __device__ __forceinline__ void row_pass(const bf16_t* y, const void* xin, void* xout, const float* g_post, const float* g_pre, bf16_t* hout, int G, int blk) {
;     ...
;         for (int j = 0; j < 8; ++j) { const f32x4 gv = gp[64 * j]; xv[j] = xv[j] + yv[j] * r * gv;
;             if (XOUT_BF) { u32x2 w; w.x = cvtpk(xv[j].x, xv[j].y); w.y = cvtpk(xv[j].z, xv[j].w); NTS(w, xob[64 * j]); } else NTS(xv[j], xo[64 * j]);
;             s1 += (xv[j].x * xv[j].x + xv[j].y * xv[j].y) + (xv[j].z * xv[j].z + xv[j].w * xv[j].w); }
;         if (HAS_H) {
;             const float r1 = 1.0f / sqrtf(wave_sum(s1) * (1.0f / DM) + EPS);
	v_pk_mul_f32 v[222:223], v[196:197], v[220:221] op_sel_hi:[1,0]
	v_pk_mul_f32 v[224:225], v[198:199], v[220:221] op_sel_hi:[1,0]
	v_pk_fma_f32 v[156:157], v[24:25], v[222:223], v[156:157]
	v_pk_fma_f32 v[158:159], v[26:27], v[224:225], v[158:159]
	v_cvt_pk_bf16_f32 v232, v156, v157
	v_cvt_pk_bf16_f32 v233, v158, v159
	v_pk_mul_f32 v[222:223], v[200:201], v[220:221] op_sel_hi:[1,0]
	v_pk_mul_f32 v[224:225], v[202:203], v[220:221] op_sel_hi:[1,0]
	v_pk_fma_f32 v[164:165], v[28:29], v[222:223], v[164:165]
	v_pk_fma_f32 v[166:167], v[30:31], v[224:225], v[166:167]
	v_cvt_pk_bf16_f32 v234, v164, v165
	v_cvt_pk_bf16_f32 v235, v166, v167
	global_store_dwordx4 v5, v[232:235], s[70:71] offset:1024 nt
	v_pk_mul_f32 v[222:223], v[204:205], v[220:221] op_sel_hi:[1,0]
	v_pk_mul_f32 v[224:225], v[206:207], v[220:221] op_sel_hi:[1,0]
	v_pk_fma_f32 v[168:169], v[32:33], v[222:223], v[168:169]
	v_pk_fma_f32 v[170:171], v[34:35], v[224:225], v[170:171]
	v_cvt_pk_bf16_f32 v228, v168, v169
	v_cvt_pk_bf16_f32 v229, v170, v171
	v_pk_mul_f32 v[222:223], v[208:209], v[220:221] op_sel_hi:[1,0]
	v_pk_mul_f32 v[224:225], v[210:211], v[220:221] op_sel_hi:[1,0]
	v_pk_fma_f32 v[172:173], v[36:37], v[222:223], v[172:173]
	v_pk_fma_f32 v[174:175], v[38:39], v[224:225], v[174:175]
	v_cvt_pk_bf16_f32 v230, v172, v173
	v_cvt_pk_bf16_f32 v231, v174, v175
	global_store_dwordx4 v5, v[228:231], s[70:71] offset:2048 nt
	v_pk_mul_f32 v[222:223], v[212:213], v[220:221] op_sel_hi:[1,0]
	v_pk_mul_f32 v[224:225], v[214:215], v[220:221] op_sel_hi:[1,0]
	v_pk_fma_f32 v[176:177], v[40:41], v[222:223], v[176:177]
	v_pk_fma_f32 v[178:179], v[42:43], v[224:225], v[178:179]
	v_cvt_pk_bf16_f32 v232, v176, v177
	v_cvt_pk_bf16_f32 v233, v178, v179
	v_pk_mul_f32 v[222:223], v[216:217], v[220:221] op_sel_hi:[1,0]
	v_pk_mul_f32 v[224:225], v[218:219], v[220:221] op_sel_hi:[1,0]
	v_pk_fma_f32 v[180:181], v[44:45], v[222:223], v[180:181]
	v_pk_fma_f32 v[182:183], v[46:47], v[224:225], v[182:183]
	v_cvt_pk_bf16_f32 v234, v180, v181
	v_cvt_pk_bf16_f32 v235, v182, v183
	global_store_dwordx4 v5, v[232:235], s[70:71] offset:3072 nt
	s_add_u32 s70, s70, s62
	s_addc_u32 s71, s71, 0
	v_pk_mul_f32 v[14:15], v[148:149], v[148:149]
	v_pk_mul_f32 v[130:131], v[150:151], v[150:151]
	v_pk_fma_f32 v[14:15], v[152:153], v[152:153], v[14:15]
	v_pk_fma_f32 v[130:131], v[154:155], v[154:155], v[130:131]
	v_pk_fma_f32 v[14:15], v[156:157], v[156:157], v[14:15]
	v_pk_fma_f32 v[130:131], v[158:159], v[158:159], v[130:131]
	v_pk_fma_f32 v[14:15], v[164:165], v[164:165], v[14:15]
	v_pk_fma_f32 v[130:131], v[166:167], v[166:167], v[130:131]
	v_pk_fma_f32 v[14:15], v[168:169], v[168:169], v[14:15]
	v_pk_fma_f32 v[130:131], v[170:171], v[170:171], v[130:131]
	v_pk_fma_f32 v[14:15], v[172:173], v[172:173], v[14:15]
	v_pk_fma_f32 v[130:131], v[174:175], v[174:175], v[130:131]
	v_pk_fma_f32 v[14:15], v[176:177], v[176:177], v[14:15]
	v_pk_fma_f32 v[130:131], v[178:179], v[178:179], v[130:131]
	v_pk_fma_f32 v[14:15], v[180:181], v[180:181], v[14:15]
	v_pk_fma_f32 v[130:131], v[182:183], v[182:183], v[130:131]
	v_pk_add_f32 v[14:15], v[14:15], v[130:131]
	s_nop 0
	v_add_f32_e32 v161, v14, v15
	ds_bpermute_b32 v188, v8, v161
	s_waitcnt lgkmcnt(0)
	v_add_f32_e32 v161, v161, v188
	ds_bpermute_b32 v188, v9, v161
	s_waitcnt lgkmcnt(0)
	v_add_f32_e32 v161, v161, v188
	ds_bpermute_b32 v188, v10, v161
	s_waitcnt lgkmcnt(0)
	v_add_f32_e32 v161, v161, v188
	ds_bpermute_b32 v188, v11, v161
	s_waitcnt lgkmcnt(0)
	v_add_f32_e32 v161, v161, v188
	ds_bpermute_b32 v188, v12, v161
	s_waitcnt lgkmcnt(0)
	v_add_f32_e32 v161, v161, v188
	ds_bpermute_b32 v188, v13, v161
	s_waitcnt lgkmcnt(0)
; __device__ __forceinline__ unsigned cvtpk(float lo, float hi) { f32x2_t v = {lo, hi}; bf16x2_t b = __builtin_convertvector(v, bf16x2_t); return __builtin_bit_cast(unsigned, b); }
; template <bool HAS_H, bool XIN_BF, bool XOUT_BF>
; __device__ __forceinline__ void row_pass(const bf16_t* y, const void* xin, void* xout, const float* g_post, const float* g_pre, bf16_t* hout, int G, int blk) {
;     ...
;             const float r1 = 1.0f / sqrtf(wave_sum(s1) * (1.0f / DM) + EPS);
;             const f32x4* gq = (const f32x4*)g_pre + lane;
;             u32x2* ho = (u32x2*)(hout + (size_t)row * DM) + lane;
; #pragma unroll
;             for (int j = 0; j < 8; ++j) { const f32x4 gv = gq[64 * j]; u32x2 w; w.x = cvtpk(xv[j].x * r1 * gv.x, xv[j].y * r1 * gv.y); w.y = cvtpk(xv[j].z * r1 * gv.z, xv[j].w * r1 * gv.w); ho[64 * j] = w; }
;         }
;     }
	v_add_f32_e32 v161, v161, v188
	v_fmamk_f32 v161, v161, 0x3a000000, v6
	v_mul_f32_e32 v189, 0x4f800000, v161
	v_cmp_gt_f32_e32 vcc, s85, v161
	s_nop 1
	v_cndmask_b32_e32 v161, v161, v189, vcc
	v_sqrt_f32_e32 v189, v161
	s_nop 0
	v_add_u32_e32 v191, -1, v189
	v_add_u32_e32 v226, 1, v189
	v_fma_f32 v227, -v191, v189, v161
	v_fma_f32 v188, -v226, v189, v161
	v_cmp_ge_f32_e64 s[80:81], 0, v227
	s_nop 1
	v_cndmask_b32_e64 v189, v189, v191, s[80:81]
	v_cmp_lt_f32_e64 s[80:81], 0, v188
	s_nop 1
	v_cndmask_b32_e64 v189, v189, v226, s[80:81]
	v_mul_f32_e32 v191, 0x37800000, v189
	v_cndmask_b32_e32 v189, v189, v191, vcc
	v_cmp_class_f32_e32 vcc, v161, v7
	s_nop 1
	v_cndmask_b32_e32 v161, v189, v161, vcc
	v_div_scale_f32 v189, s[80:81], v161, v161, 1.0
	v_rcp_f32_e32 v226, v189
	v_div_scale_f32 v191, vcc, 1.0, v161, 1.0
	v_fma_f32 v227, -v189, v226, 1.0
	v_fmac_f32_e32 v226, v227, v226
	v_mul_f32_e32 v227, v191, v226
	v_fma_f32 v188, -v189, v227, v191
	v_fmac_f32_e32 v227, v188, v226
	v_fma_f32 v189, -v189, v227, v191
	v_div_fmas_f32 v189, v189, v226, v227
	v_div_fixup_f32 v220, v189, v161, 1.0
	v_pk_mul_f32 v[222:223], v[148:149], v[220:221] op_sel_hi:[1,0]
	v_pk_mul_f32 v[224:225], v[150:151], v[220:221] op_sel_hi:[1,0]
	v_pk_mul_f32 v[222:223], v[48:49], v[222:223]
	v_pk_mul_f32 v[224:225], v[50:51], v[224:225]
	v_cvt_pk_bf16_f32 v228, v222, v223
	v_cvt_pk_bf16_f32 v229, v224, v225
	v_pk_mul_f32 v[222:223], v[152:153], v[220:221] op_sel_hi:[1,0]
	v_pk_mul_f32 v[224:225], v[154:155], v[220:221] op_sel_hi:[1,0]
	v_pk_mul_f32 v[222:223], v[52:53], v[222:223]
	v_pk_mul_f32 v[224:225], v[54:55], v[224:225]
	v_cvt_pk_bf16_f32 v230, v222, v223
	v_cvt_pk_bf16_f32 v231, v224, v225
	global_store_dwordx4 v5, v[228:231], s[78:79] offset:0
	v_pk_mul_f32 v[222:223], v[156:157], v[220:221] op_sel_hi:[1,0]
	v_pk_mul_f32 v[224:225], v[158:159], v[220:221] op_sel_hi:[1,0]
	v_pk_mul_f32 v[222:223], v[56:57], v[222:223]
	v_pk_mul_f32 v[224:225], v[58:59], v[224:225]
	v_cvt_pk_bf16_f32 v232, v222, v223
	v_cvt_pk_bf16_f32 v233, v224, v225
	v_pk_mul_f32 v[222:223], v[164:165], v[220:221] op_sel_hi:[1,0]
	v_pk_mul_f32 v[224:225], v[166:167], v[220:221] op_sel_hi:[1,0]
	v_pk_mul_f32 v[222:223], v[60:61], v[222:223]
	v_pk_mul_f32 v[224:225], v[62:63], v[224:225]
	v_cvt_pk_bf16_f32 v234, v222, v223
	v_cvt_pk_bf16_f32 v235, v224, v225
	global_store_dwordx4 v5, v[232:235], s[78:79] offset:1024
	v_pk_mul_f32 v[222:223], v[168:169], v[220:221] op_sel_hi:[1,0]
	v_pk_mul_f32 v[224:225], v[170:171], v[220:221] op_sel_hi:[1,0]
	v_pk_mul_f32 v[222:223], v[64:65], v[222:223]
	v_pk_mul_f32 v[224:225], v[66:67], v[224:225]
	v_cvt_pk_bf16_f32 v228, v222, v223
	v_cvt_pk_bf16_f32 v229, v224, v225
	v_pk_mul_f32 v[222:223], v[172:173], v[220:221] op_sel_hi:[1,0]
	v_pk_mul_f32 v[224:225], v[174:175], v[220:221] op_sel_hi:[1,0]
	v_pk_mul_f32 v[222:223], v[68:69], v[222:223]
	v_pk_mul_f32 v[224:225], v[70:71], v[224:225]
	v_cvt_pk_bf16_f32 v230, v222, v223
	v_cvt_pk_bf16_f32 v231, v224, v225
	global_store_dwordx4 v5, v[228:231], s[78:79] offset:2048
	v_pk_mul_f32 v[222:223], v[176:177], v[220:221] op_sel_hi:[1,0]
	v_pk_mul_f32 v[224:225], v[178:179], v[220:221] op_sel_hi:[1,0]
	v_pk_mul_f32 v[222:223], v[72:73], v[222:223]
	v_pk_mul_f32 v[224:225], v[74:75], v[224:225]
	v_cvt_pk_bf16_f32 v232, v222, v223
	v_cvt_pk_bf16_f32 v233, v224, v225
	v_pk_mul_f32 v[222:223], v[180:181], v[220:221] op_sel_hi:[1,0]
	v_pk_mul_f32 v[224:225], v[182:183], v[220:221] op_sel_hi:[1,0]
	v_pk_mul_f32 v[222:223], v[76:77], v[222:223]
	v_pk_mul_f32 v[224:225], v[78:79], v[224:225]
	v_cvt_pk_bf16_f32 v234, v222, v223
	v_cvt_pk_bf16_f32 v235, v224, v225
	global_store_dwordx4 v5, v[232:235], s[78:79] offset:3072
	s_add_u32 s78, s78, s62
	s_addc_u32 s79, s79, 0
	s_mov_b32 s32, s84
	s_cmp_lt_u32 s32, 0x8000
	s_cbranch_scc1 .Lrow_rp2_top
